# EpiResid: f32 stores as full 128B lines via DPP row exchange, bf16 copy stored 16B per lane via permlane16_swap
# speedup vs baseline: 1.0172x; 1.0172x over previous
; __device__ __forceinline__ unsigned cvt_pk_bf16(float lo, float hi) { unsigned r; asm volatile("v_cvt_pk_bf16_f32 %0, %1, %2" : "=v"(r) : "v"(lo), "v"(hi)); return r; }
;     __device__ __forceinline__ void operator()(const f32x4 (&acc)[2][2][4][2], const Unit& u, int wr, int wc, int fr, int fq) const {
;         const int row0 = u.pm * BM + wr * 64 + fr, col0 = u.pn * BM + wc * 32 + 4 * fq;
;         f32x4 bs[2][4];
; #pragma unroll
;         for (int q = 0; q < 4; ++q) bs[0][q] = *(const f32x4*)(xin + (size_t)row0 * ldc + col0 + (q >> 1) * HALF + (q & 1) * 16);
; #pragma unroll
;         for (int gi = 0; gi < 8; ++gi) {
;             const int ai = gi >> 2, m = gi & 3;
;             const int row = row0 + ai * HALF + m * 16;
;             const size_t off = (size_t)row * ldc + col0;
;             if (gi + 1 < 8) {
;                 const size_t offn = (size_t)(row0 + ((gi + 1) >> 2) * HALF + ((gi + 1) & 3) * 16) * ldc + col0;
; #pragma unroll
;                 for (int q = 0; q < 4; ++q) bs[(gi + 1) & 1][q] = *(const f32x4*)(xin + offn + (q >> 1) * HALF + (q & 1) * 16);
;             }
;             float sq = 0.f;
; #pragma unroll
;             for (int q = 0; q < 4; ++q) {
;                 const int bj = q >> 1, n = q & 1;
;                 const f32x4 o = bs[gi & 1][q] + acc[ai][bj][m][n];
;                 *(f32x4*)(out + off + bj * HALF + n * 16) = o;
;                 if (ss) {
;                     u32x2 w; w.x = cvt_pk_bf16(o[0], o[1]); w.y = cvt_pk_bf16(o[2], o[3]);
;                     *(u32x2*)(xb + off + bj * HALF + n * 16) = w;
;                     sq += (o[0] * o[0] + o[1] * o[1]) + (o[2] * o[2] + o[3] * o[3]);
;                 }
;             }
;             if (ss) { sq += __shfl_xor(sq, 16); sq += __shfl_xor(sq, 32); if (fq == 0) ss[(size_t)row * 32 + u.pn * 4 + wc] = sq; }
.LBB0_345:
	s_andn2_b64 vcc, exec, s[26:27]
	s_cbranch_vccnz .Lres_noss
	v_lshl_add_u32 v246, s55, 8, v188
	v_lshl_or_b32 v247, s2, 8, v190
	v_lshlrev_b32_e32 v247, 2, v247
	v_lshl_add_u32 v160, v246, 13, v247
	v_add_u32_e32 v161, 0x20000, v160
	v_add_u32_e32 v162, 0x40000, v160
	v_add_u32_e32 v163, 0x60000, v160
	v_add_u32_e32 v164, 0x100000, v160
	v_add_u32_e32 v165, 0x120000, v160
	v_add_u32_e32 v192, 0x140000, v160
	v_add_u32_e32 v193, 0x160000, v160
	global_load_dwordx4 v[128:131], v160, s[14:15]
	global_load_dwordx4 v[132:135], v160, s[14:15] offset:64
	global_load_dwordx4 v[136:139], v160, s[14:15] offset:512
	global_load_dwordx4 v[140:143], v160, s[14:15] offset:576
	global_load_dwordx4 v[144:147], v161, s[14:15]
	global_load_dwordx4 v[148:151], v161, s[14:15] offset:64
	global_load_dwordx4 v[152:155], v161, s[14:15] offset:512
	global_load_dwordx4 v[156:159], v161, s[14:15] offset:576
	global_load_dwordx4 v[206:209], v162, s[14:15]
	global_load_dwordx4 v[210:213], v162, s[14:15] offset:64
	global_load_dwordx4 v[214:217], v162, s[14:15] offset:512
	global_load_dwordx4 v[218:221], v162, s[14:15] offset:576
	s_lshl_b32 s34, s2, 4
	s_lshl_b32 s35, s46, 2
	s_add_i32 s34, s34, s35
	v_lshl_add_u32 v189, v246, 7, s34
	v_and_b32_e32 v246, 8, v188
	v_mov_b32_e32 v247, 0x10040
	v_cmp_eq_u32_e32 vcc, 0, v246
	s_nop 1
	v_mov_b32_e32 v246, 0xffff0040
	v_cndmask_b32_e32 v234, v246, v169, vcc
	v_cndmask_b32_e32 v235, 0, v247, vcc
	v_and_b32_e32 v245, 4, v190
	v_mul_u32_u24_e32 v245, 6, v245
	s_waitcnt vmcnt(8)
	v_pk_add_f32 v[124:125], v[128:129], v[124:125]
	v_pk_add_f32 v[126:127], v[130:131], v[126:127]
	v_pk_add_f32 v[120:121], v[132:133], v[120:121]
	v_pk_add_f32 v[122:123], v[134:135], v[122:123]
	v_pk_add_f32 v[116:117], v[136:137], v[116:117]
	v_pk_add_f32 v[118:119], v[138:139], v[118:119]
	v_pk_add_f32 v[108:109], v[140:141], v[108:109]
	v_pk_add_f32 v[110:111], v[142:143], v[110:111]
	global_load_dwordx4 v[128:131], v163, s[14:15]
	global_load_dwordx4 v[132:135], v163, s[14:15] offset:64
	global_load_dwordx4 v[136:139], v163, s[14:15] offset:512
	global_load_dwordx4 v[140:143], v163, s[14:15] offset:576
	v_add_u32_e32 v236, v160, v234
	v_add_u32_e32 v237, v160, v235
	v_mov_b32_dpp v222, v120 row_ror:8 row_mask:0xf bank_mask:0xf
	v_mov_b32_dpp v223, v121 row_ror:8 row_mask:0xf bank_mask:0xf
	v_mov_b32_dpp v224, v122 row_ror:8 row_mask:0xf bank_mask:0xf
	v_mov_b32_dpp v225, v123 row_ror:8 row_mask:0xf bank_mask:0xf
	v_cndmask_b32_e32 v226, v222, v124, vcc
	v_cndmask_b32_e32 v227, v223, v125, vcc
	v_cndmask_b32_e32 v228, v224, v126, vcc
	v_cndmask_b32_e32 v229, v225, v127, vcc
	v_cndmask_b32_e32 v230, v124, v222, vcc
	v_cndmask_b32_e32 v231, v125, v223, vcc
	v_cndmask_b32_e32 v232, v126, v224, vcc
	v_cndmask_b32_e32 v233, v127, v225, vcc
	global_store_dwordx4 v236, v[226:229], s[72:73]
	global_store_dwordx4 v237, v[230:233], s[72:73]
	v_mov_b32_dpp v222, v108 row_ror:8 row_mask:0xf bank_mask:0xf
	v_mov_b32_dpp v223, v109 row_ror:8 row_mask:0xf bank_mask:0xf
	v_mov_b32_dpp v224, v110 row_ror:8 row_mask:0xf bank_mask:0xf
	v_mov_b32_dpp v225, v111 row_ror:8 row_mask:0xf bank_mask:0xf
	v_cndmask_b32_e32 v226, v222, v116, vcc
	v_cndmask_b32_e32 v227, v223, v117, vcc
	v_cndmask_b32_e32 v228, v224, v118, vcc
	v_cndmask_b32_e32 v229, v225, v119, vcc
	v_cndmask_b32_e32 v230, v116, v222, vcc
	v_cndmask_b32_e32 v231, v117, v223, vcc
	v_cndmask_b32_e32 v232, v118, v224, vcc
	v_cndmask_b32_e32 v233, v119, v225, vcc
	global_store_dwordx4 v236, v[226:229], s[72:73] offset:512
	global_store_dwordx4 v237, v[230:233], s[72:73] offset:512
	v_lshrrev_b32_e32 v236, 1, v160
	v_add_u32_e32 v236, v236, v245
	v_cvt_pk_bf16_f32 v194, v124, v125
	v_cvt_pk_bf16_f32 v195, v126, v127
	v_mul_f32_e32 v246, v125, v125
	v_mul_f32_e32 v247, v127, v127
	v_fmac_f32_e32 v246, v124, v124
	v_fmac_f32_e32 v247, v126, v126
	v_add_f32_e32 v180, v246, v247
	v_cvt_pk_bf16_f32 v196, v120, v121
	v_cvt_pk_bf16_f32 v197, v122, v123
	v_mul_f32_e32 v246, v121, v121
	v_mul_f32_e32 v247, v123, v123
	v_fmac_f32_e32 v246, v120, v120
	v_fmac_f32_e32 v247, v122, v122
	v_add_f32_e32 v246, v246, v247
	v_add_f32_e32 v180, v246, v180
	v_permlane16_swap_b32_e32 v194, v196
	v_permlane16_swap_b32_e32 v195, v197
	global_store_dwordx4 v236, v[194:197], s[22:23]
	s_nop 1
	v_cvt_pk_bf16_f32 v194, v116, v117
	v_cvt_pk_bf16_f32 v195, v118, v119
	v_mul_f32_e32 v246, v117, v117
	v_mul_f32_e32 v247, v119, v119
	v_fmac_f32_e32 v246, v116, v116
	v_fmac_f32_e32 v247, v118, v118
	v_add_f32_e32 v246, v246, v247
	v_add_f32_e32 v180, v246, v180
	v_cvt_pk_bf16_f32 v196, v108, v109
	v_cvt_pk_bf16_f32 v197, v110, v111
	v_mul_f32_e32 v246, v109, v109
	v_mul_f32_e32 v247, v111, v111
	v_fmac_f32_e32 v246, v108, v108
	v_fmac_f32_e32 v247, v110, v110
	v_add_f32_e32 v246, v246, v247
	v_add_f32_e32 v180, v246, v180
	v_permlane16_swap_b32_e32 v194, v196
	v_permlane16_swap_b32_e32 v195, v197
	global_store_dwordx4 v236, v[194:197], s[22:23] offset:256
	s_nop 1
	s_waitcnt vmcnt(14)
; __device__ __forceinline__ unsigned cvt_pk_bf16(float lo, float hi) { unsigned r; asm volatile("v_cvt_pk_bf16_f32 %0, %1, %2" : "=v"(r) : "v"(lo), "v"(hi)); return r; }
;     __device__ __forceinline__ void operator()(const f32x4 (&acc)[2][2][4][2], const Unit& u, int wr, int wc, int fr, int fq) const {
;     ...
;         for (int gi = 0; gi < 8; ++gi) {
;             const int ai = gi >> 2, m = gi & 3;
;             const int row = row0 + ai * HALF + m * 16;
;             const size_t off = (size_t)row * ldc + col0;
;             if (gi + 1 < 8) {
;                 const size_t offn = (size_t)(row0 + ((gi + 1) >> 2) * HALF + ((gi + 1) & 3) * 16) * ldc + col0;
; #pragma unroll
;                 for (int q = 0; q < 4; ++q) bs[(gi + 1) & 1][q] = *(const f32x4*)(xin + offn + (q >> 1) * HALF + (q & 1) * 16);
;             }
;             float sq = 0.f;
; #pragma unroll
;             for (int q = 0; q < 4; ++q) {
;                 const int bj = q >> 1, n = q & 1;
;                 const f32x4 o = bs[gi & 1][q] + acc[ai][bj][m][n];
;                 *(f32x4*)(out + off + bj * HALF + n * 16) = o;
;                 if (ss) {
;                     u32x2 w; w.x = cvt_pk_bf16(o[0], o[1]); w.y = cvt_pk_bf16(o[2], o[3]);
;                     *(u32x2*)(xb + off + bj * HALF + n * 16) = w;
;                     sq += (o[0] * o[0] + o[1] * o[1]) + (o[2] * o[2] + o[3] * o[3]);
;                 }
;             }
;             if (ss) { sq += __shfl_xor(sq, 16); sq += __shfl_xor(sq, 32); if (fq == 0) ss[(size_t)row * 32 + u.pn * 4 + wc] = sq; }
	v_pk_add_f32 v[112:113], v[144:145], v[112:113]
	v_pk_add_f32 v[114:115], v[146:147], v[114:115]
	v_pk_add_f32 v[104:105], v[148:149], v[104:105]
	v_pk_add_f32 v[106:107], v[150:151], v[106:107]
	v_pk_add_f32 v[100:101], v[152:153], v[100:101]
	v_pk_add_f32 v[102:103], v[154:155], v[102:103]
	v_pk_add_f32 v[92:93], v[156:157], v[92:93]
	v_pk_add_f32 v[94:95], v[158:159], v[94:95]
	global_load_dwordx4 v[144:147], v164, s[14:15]
	global_load_dwordx4 v[148:151], v164, s[14:15] offset:64
	global_load_dwordx4 v[152:155], v164, s[14:15] offset:512
	global_load_dwordx4 v[156:159], v164, s[14:15] offset:576
	v_add_u32_e32 v236, v161, v234
	v_add_u32_e32 v237, v161, v235
	v_mov_b32_dpp v222, v104 row_ror:8 row_mask:0xf bank_mask:0xf
	v_mov_b32_dpp v223, v105 row_ror:8 row_mask:0xf bank_mask:0xf
	v_mov_b32_dpp v224, v106 row_ror:8 row_mask:0xf bank_mask:0xf
	v_mov_b32_dpp v225, v107 row_ror:8 row_mask:0xf bank_mask:0xf
	v_cndmask_b32_e32 v226, v222, v112, vcc
	v_cndmask_b32_e32 v227, v223, v113, vcc
	v_cndmask_b32_e32 v228, v224, v114, vcc
	v_cndmask_b32_e32 v229, v225, v115, vcc
	v_cndmask_b32_e32 v230, v112, v222, vcc
	v_cndmask_b32_e32 v231, v113, v223, vcc
	v_cndmask_b32_e32 v232, v114, v224, vcc
	v_cndmask_b32_e32 v233, v115, v225, vcc
	global_store_dwordx4 v236, v[226:229], s[72:73]
	global_store_dwordx4 v237, v[230:233], s[72:73]
	v_mov_b32_dpp v222, v92 row_ror:8 row_mask:0xf bank_mask:0xf
	v_mov_b32_dpp v223, v93 row_ror:8 row_mask:0xf bank_mask:0xf
	v_mov_b32_dpp v224, v94 row_ror:8 row_mask:0xf bank_mask:0xf
	v_mov_b32_dpp v225, v95 row_ror:8 row_mask:0xf bank_mask:0xf
	v_cndmask_b32_e32 v226, v222, v100, vcc
	v_cndmask_b32_e32 v227, v223, v101, vcc
	v_cndmask_b32_e32 v228, v224, v102, vcc
	v_cndmask_b32_e32 v229, v225, v103, vcc
	v_cndmask_b32_e32 v230, v100, v222, vcc
	v_cndmask_b32_e32 v231, v101, v223, vcc
	v_cndmask_b32_e32 v232, v102, v224, vcc
	v_cndmask_b32_e32 v233, v103, v225, vcc
	global_store_dwordx4 v236, v[226:229], s[72:73] offset:512
	global_store_dwordx4 v237, v[230:233], s[72:73] offset:512
	v_lshrrev_b32_e32 v236, 1, v161
	v_add_u32_e32 v236, v236, v245
	v_cvt_pk_bf16_f32 v194, v112, v113
	v_cvt_pk_bf16_f32 v195, v114, v115
	v_mul_f32_e32 v246, v113, v113
	v_mul_f32_e32 v247, v115, v115
	v_fmac_f32_e32 v246, v112, v112
	v_fmac_f32_e32 v247, v114, v114
	v_add_f32_e32 v181, v246, v247
	v_cvt_pk_bf16_f32 v196, v104, v105
	v_cvt_pk_bf16_f32 v197, v106, v107
	v_mul_f32_e32 v246, v105, v105
	v_mul_f32_e32 v247, v107, v107
	v_fmac_f32_e32 v246, v104, v104
	v_fmac_f32_e32 v247, v106, v106
	v_add_f32_e32 v246, v246, v247
	v_add_f32_e32 v181, v246, v181
	v_permlane16_swap_b32_e32 v194, v196
	v_permlane16_swap_b32_e32 v195, v197
	global_store_dwordx4 v236, v[194:197], s[22:23]
	s_nop 1
	v_cvt_pk_bf16_f32 v194, v100, v101
	v_cvt_pk_bf16_f32 v195, v102, v103
	v_mul_f32_e32 v246, v101, v101
	v_mul_f32_e32 v247, v103, v103
	v_fmac_f32_e32 v246, v100, v100
	v_fmac_f32_e32 v247, v102, v102
	v_add_f32_e32 v246, v246, v247
	v_add_f32_e32 v181, v246, v181
	v_cvt_pk_bf16_f32 v196, v92, v93
	v_cvt_pk_bf16_f32 v197, v94, v95
	v_mul_f32_e32 v246, v93, v93
	v_mul_f32_e32 v247, v95, v95
	v_fmac_f32_e32 v246, v92, v92
	v_fmac_f32_e32 v247, v94, v94
	v_add_f32_e32 v246, v246, v247
	v_add_f32_e32 v181, v246, v181
	v_permlane16_swap_b32_e32 v194, v196
	v_permlane16_swap_b32_e32 v195, v197
	global_store_dwordx4 v236, v[194:197], s[22:23] offset:256
	s_nop 1
	s_waitcnt vmcnt(20)
	v_pk_add_f32 v[96:97], v[206:207], v[96:97]
	v_pk_add_f32 v[98:99], v[208:209], v[98:99]
	v_pk_add_f32 v[88:89], v[210:211], v[88:89]
	v_pk_add_f32 v[90:91], v[212:213], v[90:91]
	v_pk_add_f32 v[84:85], v[214:215], v[84:85]
	v_pk_add_f32 v[86:87], v[216:217], v[86:87]
	v_pk_add_f32 v[76:77], v[218:219], v[76:77]
	v_pk_add_f32 v[78:79], v[220:221], v[78:79]
	global_load_dwordx4 v[206:209], v165, s[14:15]
	global_load_dwordx4 v[210:213], v165, s[14:15] offset:64
	global_load_dwordx4 v[214:217], v165, s[14:15] offset:512
	global_load_dwordx4 v[218:221], v165, s[14:15] offset:576
	v_add_u32_e32 v236, v162, v234
	v_add_u32_e32 v237, v162, v235
	v_mov_b32_dpp v222, v88 row_ror:8 row_mask:0xf bank_mask:0xf
	v_mov_b32_dpp v223, v89 row_ror:8 row_mask:0xf bank_mask:0xf
	v_mov_b32_dpp v224, v90 row_ror:8 row_mask:0xf bank_mask:0xf
	v_mov_b32_dpp v225, v91 row_ror:8 row_mask:0xf bank_mask:0xf
	v_cndmask_b32_e32 v226, v222, v96, vcc
	v_cndmask_b32_e32 v227, v223, v97, vcc
	v_cndmask_b32_e32 v228, v224, v98, vcc
	v_cndmask_b32_e32 v229, v225, v99, vcc
	v_cndmask_b32_e32 v230, v96, v222, vcc
	v_cndmask_b32_e32 v231, v97, v223, vcc
	v_cndmask_b32_e32 v232, v98, v224, vcc
	v_cndmask_b32_e32 v233, v99, v225, vcc
	global_store_dwordx4 v236, v[226:229], s[72:73]
	global_store_dwordx4 v237, v[230:233], s[72:73]
	v_mov_b32_dpp v222, v76 row_ror:8 row_mask:0xf bank_mask:0xf
	v_mov_b32_dpp v223, v77 row_ror:8 row_mask:0xf bank_mask:0xf
	v_mov_b32_dpp v224, v78 row_ror:8 row_mask:0xf bank_mask:0xf
	v_mov_b32_dpp v225, v79 row_ror:8 row_mask:0xf bank_mask:0xf
	v_cndmask_b32_e32 v226, v222, v84, vcc
	v_cndmask_b32_e32 v227, v223, v85, vcc
	v_cndmask_b32_e32 v228, v224, v86, vcc
	v_cndmask_b32_e32 v229, v225, v87, vcc
	v_cndmask_b32_e32 v230, v84, v222, vcc
	v_cndmask_b32_e32 v231, v85, v223, vcc
	v_cndmask_b32_e32 v232, v86, v224, vcc
	v_cndmask_b32_e32 v233, v87, v225, vcc
	global_store_dwordx4 v236, v[226:229], s[72:73] offset:512
	global_store_dwordx4 v237, v[230:233], s[72:73] offset:512
	v_lshrrev_b32_e32 v236, 1, v162
	v_add_u32_e32 v236, v236, v245
	v_cvt_pk_bf16_f32 v194, v96, v97
	v_cvt_pk_bf16_f32 v195, v98, v99
	v_mul_f32_e32 v246, v97, v97
	v_mul_f32_e32 v247, v99, v99
	v_fmac_f32_e32 v246, v96, v96
	v_fmac_f32_e32 v247, v98, v98
	v_add_f32_e32 v182, v246, v247
	v_cvt_pk_bf16_f32 v196, v88, v89
	v_cvt_pk_bf16_f32 v197, v90, v91
	v_mul_f32_e32 v246, v89, v89
	v_mul_f32_e32 v247, v91, v91
	v_fmac_f32_e32 v246, v88, v88
	v_fmac_f32_e32 v247, v90, v90
	v_add_f32_e32 v246, v246, v247
	v_add_f32_e32 v182, v246, v182
	v_permlane16_swap_b32_e32 v194, v196
	v_permlane16_swap_b32_e32 v195, v197
	global_store_dwordx4 v236, v[194:197], s[22:23]
	s_nop 1
	v_cvt_pk_bf16_f32 v194, v84, v85
	v_cvt_pk_bf16_f32 v195, v86, v87
	v_mul_f32_e32 v246, v85, v85
	v_mul_f32_e32 v247, v87, v87
	v_fmac_f32_e32 v246, v84, v84
	v_fmac_f32_e32 v247, v86, v86
	v_add_f32_e32 v246, v246, v247
	v_add_f32_e32 v182, v246, v182
	v_cvt_pk_bf16_f32 v196, v76, v77
	v_cvt_pk_bf16_f32 v197, v78, v79
	v_mul_f32_e32 v246, v77, v77
	v_mul_f32_e32 v247, v79, v79
	v_fmac_f32_e32 v246, v76, v76
	v_fmac_f32_e32 v247, v78, v78
	v_add_f32_e32 v246, v246, v247
	v_add_f32_e32 v182, v246, v182
	v_permlane16_swap_b32_e32 v194, v196
	v_permlane16_swap_b32_e32 v195, v197
	global_store_dwordx4 v236, v[194:197], s[22:23] offset:256
	s_nop 1
	s_waitcnt vmcnt(26)
; __device__ __forceinline__ unsigned cvt_pk_bf16(float lo, float hi) { unsigned r; asm volatile("v_cvt_pk_bf16_f32 %0, %1, %2" : "=v"(r) : "v"(lo), "v"(hi)); return r; }
;     __device__ __forceinline__ void operator()(const f32x4 (&acc)[2][2][4][2], const Unit& u, int wr, int wc, int fr, int fq) const {
;     ...
;         for (int gi = 0; gi < 8; ++gi) {
;             const int ai = gi >> 2, m = gi & 3;
;             const int row = row0 + ai * HALF + m * 16;
;             const size_t off = (size_t)row * ldc + col0;
;             if (gi + 1 < 8) {
;                 const size_t offn = (size_t)(row0 + ((gi + 1) >> 2) * HALF + ((gi + 1) & 3) * 16) * ldc + col0;
; #pragma unroll
;                 for (int q = 0; q < 4; ++q) bs[(gi + 1) & 1][q] = *(const f32x4*)(xin + offn + (q >> 1) * HALF + (q & 1) * 16);
;             }
;             float sq = 0.f;
; #pragma unroll
;             for (int q = 0; q < 4; ++q) {
;                 const int bj = q >> 1, n = q & 1;
;                 const f32x4 o = bs[gi & 1][q] + acc[ai][bj][m][n];
;                 *(f32x4*)(out + off + bj * HALF + n * 16) = o;
;                 if (ss) {
;                     u32x2 w; w.x = cvt_pk_bf16(o[0], o[1]); w.y = cvt_pk_bf16(o[2], o[3]);
;                     *(u32x2*)(xb + off + bj * HALF + n * 16) = w;
;                     sq += (o[0] * o[0] + o[1] * o[1]) + (o[2] * o[2] + o[3] * o[3]);
;                 }
;             }
;             if (ss) { sq += __shfl_xor(sq, 16); sq += __shfl_xor(sq, 32); if (fq == 0) ss[(size_t)row * 32 + u.pn * 4 + wc] = sq; }
	v_pk_add_f32 v[80:81], v[128:129], v[80:81]
	v_pk_add_f32 v[82:83], v[130:131], v[82:83]
	v_pk_add_f32 v[72:73], v[132:133], v[72:73]
	v_pk_add_f32 v[74:75], v[134:135], v[74:75]
	v_pk_add_f32 v[68:69], v[136:137], v[68:69]
	v_pk_add_f32 v[70:71], v[138:139], v[70:71]
	v_pk_add_f32 v[64:65], v[140:141], v[64:65]
	v_pk_add_f32 v[66:67], v[142:143], v[66:67]
	global_load_dwordx4 v[128:131], v192, s[14:15]
	global_load_dwordx4 v[132:135], v192, s[14:15] offset:64
	global_load_dwordx4 v[136:139], v192, s[14:15] offset:512
	global_load_dwordx4 v[140:143], v192, s[14:15] offset:576
	v_add_u32_e32 v236, v163, v234
	v_add_u32_e32 v237, v163, v235
	v_mov_b32_dpp v222, v72 row_ror:8 row_mask:0xf bank_mask:0xf
	v_mov_b32_dpp v223, v73 row_ror:8 row_mask:0xf bank_mask:0xf
	v_mov_b32_dpp v224, v74 row_ror:8 row_mask:0xf bank_mask:0xf
	v_mov_b32_dpp v225, v75 row_ror:8 row_mask:0xf bank_mask:0xf
	v_cndmask_b32_e32 v226, v222, v80, vcc
	v_cndmask_b32_e32 v227, v223, v81, vcc
	v_cndmask_b32_e32 v228, v224, v82, vcc
	v_cndmask_b32_e32 v229, v225, v83, vcc
	v_cndmask_b32_e32 v230, v80, v222, vcc
	v_cndmask_b32_e32 v231, v81, v223, vcc
	v_cndmask_b32_e32 v232, v82, v224, vcc
	v_cndmask_b32_e32 v233, v83, v225, vcc
	global_store_dwordx4 v236, v[226:229], s[72:73]
	global_store_dwordx4 v237, v[230:233], s[72:73]
	v_mov_b32_dpp v222, v64 row_ror:8 row_mask:0xf bank_mask:0xf
	v_mov_b32_dpp v223, v65 row_ror:8 row_mask:0xf bank_mask:0xf
	v_mov_b32_dpp v224, v66 row_ror:8 row_mask:0xf bank_mask:0xf
	v_mov_b32_dpp v225, v67 row_ror:8 row_mask:0xf bank_mask:0xf
	v_cndmask_b32_e32 v226, v222, v68, vcc
	v_cndmask_b32_e32 v227, v223, v69, vcc
	v_cndmask_b32_e32 v228, v224, v70, vcc
	v_cndmask_b32_e32 v229, v225, v71, vcc
	v_cndmask_b32_e32 v230, v68, v222, vcc
	v_cndmask_b32_e32 v231, v69, v223, vcc
	v_cndmask_b32_e32 v232, v70, v224, vcc
	v_cndmask_b32_e32 v233, v71, v225, vcc
	global_store_dwordx4 v236, v[226:229], s[72:73] offset:512
	global_store_dwordx4 v237, v[230:233], s[72:73] offset:512
	v_lshrrev_b32_e32 v236, 1, v163
	v_add_u32_e32 v236, v236, v245
	v_cvt_pk_bf16_f32 v194, v80, v81
	v_cvt_pk_bf16_f32 v195, v82, v83
	v_mul_f32_e32 v246, v81, v81
	v_mul_f32_e32 v247, v83, v83
	v_fmac_f32_e32 v246, v80, v80
	v_fmac_f32_e32 v247, v82, v82
	v_add_f32_e32 v183, v246, v247
	v_cvt_pk_bf16_f32 v196, v72, v73
	v_cvt_pk_bf16_f32 v197, v74, v75
	v_mul_f32_e32 v246, v73, v73
	v_mul_f32_e32 v247, v75, v75
	v_fmac_f32_e32 v246, v72, v72
	v_fmac_f32_e32 v247, v74, v74
	v_add_f32_e32 v246, v246, v247
	v_add_f32_e32 v183, v246, v183
	v_permlane16_swap_b32_e32 v194, v196
	v_permlane16_swap_b32_e32 v195, v197
	global_store_dwordx4 v236, v[194:197], s[22:23]
	s_nop 1
	v_cvt_pk_bf16_f32 v194, v68, v69
	v_cvt_pk_bf16_f32 v195, v70, v71
	v_mul_f32_e32 v246, v69, v69
	v_mul_f32_e32 v247, v71, v71
	v_fmac_f32_e32 v246, v68, v68
	v_fmac_f32_e32 v247, v70, v70
	v_add_f32_e32 v246, v246, v247
	v_add_f32_e32 v183, v246, v183
	v_cvt_pk_bf16_f32 v196, v64, v65
	v_cvt_pk_bf16_f32 v197, v66, v67
	v_mul_f32_e32 v246, v65, v65
	v_mul_f32_e32 v247, v67, v67
	v_fmac_f32_e32 v246, v64, v64
	v_fmac_f32_e32 v247, v66, v66
	v_add_f32_e32 v246, v246, v247
	v_add_f32_e32 v183, v246, v183
	v_permlane16_swap_b32_e32 v194, v196
	v_permlane16_swap_b32_e32 v195, v197
	global_store_dwordx4 v236, v[194:197], s[22:23] offset:256
	s_nop 1
	s_waitcnt vmcnt(26)
	v_pk_add_f32 v[60:61], v[144:145], v[60:61]
	v_pk_add_f32 v[62:63], v[146:147], v[62:63]
	v_pk_add_f32 v[56:57], v[148:149], v[56:57]
	v_pk_add_f32 v[58:59], v[150:151], v[58:59]
	v_pk_add_f32 v[52:53], v[152:153], v[52:53]
	v_pk_add_f32 v[54:55], v[154:155], v[54:55]
	v_pk_add_f32 v[44:45], v[156:157], v[44:45]
	v_pk_add_f32 v[46:47], v[158:159], v[46:47]
	global_load_dwordx4 v[144:147], v193, s[14:15]
	global_load_dwordx4 v[148:151], v193, s[14:15] offset:64
	global_load_dwordx4 v[152:155], v193, s[14:15] offset:512
	global_load_dwordx4 v[156:159], v193, s[14:15] offset:576
	v_add_u32_e32 v236, v164, v234
	v_add_u32_e32 v237, v164, v235
	v_mov_b32_dpp v222, v56 row_ror:8 row_mask:0xf bank_mask:0xf
	v_mov_b32_dpp v223, v57 row_ror:8 row_mask:0xf bank_mask:0xf
	v_mov_b32_dpp v224, v58 row_ror:8 row_mask:0xf bank_mask:0xf
	v_mov_b32_dpp v225, v59 row_ror:8 row_mask:0xf bank_mask:0xf
	v_cndmask_b32_e32 v226, v222, v60, vcc
	v_cndmask_b32_e32 v227, v223, v61, vcc
	v_cndmask_b32_e32 v228, v224, v62, vcc
	v_cndmask_b32_e32 v229, v225, v63, vcc
	v_cndmask_b32_e32 v230, v60, v222, vcc
	v_cndmask_b32_e32 v231, v61, v223, vcc
	v_cndmask_b32_e32 v232, v62, v224, vcc
	v_cndmask_b32_e32 v233, v63, v225, vcc
	global_store_dwordx4 v236, v[226:229], s[72:73]
	global_store_dwordx4 v237, v[230:233], s[72:73]
	v_mov_b32_dpp v222, v44 row_ror:8 row_mask:0xf bank_mask:0xf
	v_mov_b32_dpp v223, v45 row_ror:8 row_mask:0xf bank_mask:0xf
	v_mov_b32_dpp v224, v46 row_ror:8 row_mask:0xf bank_mask:0xf
	v_mov_b32_dpp v225, v47 row_ror:8 row_mask:0xf bank_mask:0xf
	v_cndmask_b32_e32 v226, v222, v52, vcc
	v_cndmask_b32_e32 v227, v223, v53, vcc
	v_cndmask_b32_e32 v228, v224, v54, vcc
	v_cndmask_b32_e32 v229, v225, v55, vcc
	v_cndmask_b32_e32 v230, v52, v222, vcc
	v_cndmask_b32_e32 v231, v53, v223, vcc
	v_cndmask_b32_e32 v232, v54, v224, vcc
	v_cndmask_b32_e32 v233, v55, v225, vcc
	global_store_dwordx4 v236, v[226:229], s[72:73] offset:512
	global_store_dwordx4 v237, v[230:233], s[72:73] offset:512
	v_lshrrev_b32_e32 v236, 1, v164
	v_add_u32_e32 v236, v236, v245
	v_cvt_pk_bf16_f32 v194, v60, v61
	v_cvt_pk_bf16_f32 v195, v62, v63
	v_mul_f32_e32 v246, v61, v61
	v_mul_f32_e32 v247, v63, v63
	v_fmac_f32_e32 v246, v60, v60
	v_fmac_f32_e32 v247, v62, v62
	v_add_f32_e32 v184, v246, v247
	v_cvt_pk_bf16_f32 v196, v56, v57
	v_cvt_pk_bf16_f32 v197, v58, v59
	v_mul_f32_e32 v246, v57, v57
	v_mul_f32_e32 v247, v59, v59
	v_fmac_f32_e32 v246, v56, v56
	v_fmac_f32_e32 v247, v58, v58
	v_add_f32_e32 v246, v246, v247
	v_add_f32_e32 v184, v246, v184
	v_permlane16_swap_b32_e32 v194, v196
	v_permlane16_swap_b32_e32 v195, v197
	global_store_dwordx4 v236, v[194:197], s[22:23]
	s_nop 1
	v_cvt_pk_bf16_f32 v194, v52, v53
	v_cvt_pk_bf16_f32 v195, v54, v55
	v_mul_f32_e32 v246, v53, v53
	v_mul_f32_e32 v247, v55, v55
	v_fmac_f32_e32 v246, v52, v52
	v_fmac_f32_e32 v247, v54, v54
	v_add_f32_e32 v246, v246, v247
	v_add_f32_e32 v184, v246, v184
	v_cvt_pk_bf16_f32 v196, v44, v45
	v_cvt_pk_bf16_f32 v197, v46, v47
	v_mul_f32_e32 v246, v45, v45
	v_mul_f32_e32 v247, v47, v47
	v_fmac_f32_e32 v246, v44, v44
	v_fmac_f32_e32 v247, v46, v46
	v_add_f32_e32 v246, v246, v247
	v_add_f32_e32 v184, v246, v184
	v_permlane16_swap_b32_e32 v194, v196
	v_permlane16_swap_b32_e32 v195, v197
	global_store_dwordx4 v236, v[194:197], s[22:23] offset:256
	s_nop 1
	s_waitcnt vmcnt(26)
; __device__ __forceinline__ unsigned cvt_pk_bf16(float lo, float hi) { unsigned r; asm volatile("v_cvt_pk_bf16_f32 %0, %1, %2" : "=v"(r) : "v"(lo), "v"(hi)); return r; }
;     __device__ __forceinline__ void operator()(const f32x4 (&acc)[2][2][4][2], const Unit& u, int wr, int wc, int fr, int fq) const {
;     ...
;         for (int gi = 0; gi < 8; ++gi) {
;             const int ai = gi >> 2, m = gi & 3;
;             const int row = row0 + ai * HALF + m * 16;
;             const size_t off = (size_t)row * ldc + col0;
;             if (gi + 1 < 8) {
;                 const size_t offn = (size_t)(row0 + ((gi + 1) >> 2) * HALF + ((gi + 1) & 3) * 16) * ldc + col0;
; #pragma unroll
;                 for (int q = 0; q < 4; ++q) bs[(gi + 1) & 1][q] = *(const f32x4*)(xin + offn + (q >> 1) * HALF + (q & 1) * 16);
;             }
;             float sq = 0.f;
; #pragma unroll
;             for (int q = 0; q < 4; ++q) {
;                 const int bj = q >> 1, n = q & 1;
;                 const f32x4 o = bs[gi & 1][q] + acc[ai][bj][m][n];
;                 *(f32x4*)(out + off + bj * HALF + n * 16) = o;
;                 if (ss) {
;                     u32x2 w; w.x = cvt_pk_bf16(o[0], o[1]); w.y = cvt_pk_bf16(o[2], o[3]);
;                     *(u32x2*)(xb + off + bj * HALF + n * 16) = w;
;                     sq += (o[0] * o[0] + o[1] * o[1]) + (o[2] * o[2] + o[3] * o[3]);
;                 }
;             }
;             if (ss) { sq += __shfl_xor(sq, 16); sq += __shfl_xor(sq, 32); if (fq == 0) ss[(size_t)row * 32 + u.pn * 4 + wc] = sq; }
	v_pk_add_f32 v[48:49], v[206:207], v[48:49]
	v_pk_add_f32 v[50:51], v[208:209], v[50:51]
	v_pk_add_f32 v[40:41], v[210:211], v[40:41]
	v_pk_add_f32 v[42:43], v[212:213], v[42:43]
	v_pk_add_f32 v[36:37], v[214:215], v[36:37]
	v_pk_add_f32 v[38:39], v[216:217], v[38:39]
	v_pk_add_f32 v[28:29], v[218:219], v[28:29]
	v_pk_add_f32 v[30:31], v[220:221], v[30:31]
	v_add_u32_e32 v236, v165, v234
	v_add_u32_e32 v237, v165, v235
	v_mov_b32_dpp v222, v40 row_ror:8 row_mask:0xf bank_mask:0xf
	v_mov_b32_dpp v223, v41 row_ror:8 row_mask:0xf bank_mask:0xf
	v_mov_b32_dpp v224, v42 row_ror:8 row_mask:0xf bank_mask:0xf
	v_mov_b32_dpp v225, v43 row_ror:8 row_mask:0xf bank_mask:0xf
	v_cndmask_b32_e32 v226, v222, v48, vcc
	v_cndmask_b32_e32 v227, v223, v49, vcc
	v_cndmask_b32_e32 v228, v224, v50, vcc
	v_cndmask_b32_e32 v229, v225, v51, vcc
	v_cndmask_b32_e32 v230, v48, v222, vcc
	v_cndmask_b32_e32 v231, v49, v223, vcc
	v_cndmask_b32_e32 v232, v50, v224, vcc
	v_cndmask_b32_e32 v233, v51, v225, vcc
	global_store_dwordx4 v236, v[226:229], s[72:73]
	global_store_dwordx4 v237, v[230:233], s[72:73]
	v_mov_b32_dpp v222, v28 row_ror:8 row_mask:0xf bank_mask:0xf
	v_mov_b32_dpp v223, v29 row_ror:8 row_mask:0xf bank_mask:0xf
	v_mov_b32_dpp v224, v30 row_ror:8 row_mask:0xf bank_mask:0xf
	v_mov_b32_dpp v225, v31 row_ror:8 row_mask:0xf bank_mask:0xf
	v_cndmask_b32_e32 v226, v222, v36, vcc
	v_cndmask_b32_e32 v227, v223, v37, vcc
	v_cndmask_b32_e32 v228, v224, v38, vcc
	v_cndmask_b32_e32 v229, v225, v39, vcc
	v_cndmask_b32_e32 v230, v36, v222, vcc
	v_cndmask_b32_e32 v231, v37, v223, vcc
	v_cndmask_b32_e32 v232, v38, v224, vcc
	v_cndmask_b32_e32 v233, v39, v225, vcc
	global_store_dwordx4 v236, v[226:229], s[72:73] offset:512
	global_store_dwordx4 v237, v[230:233], s[72:73] offset:512
	v_lshrrev_b32_e32 v236, 1, v165
	v_add_u32_e32 v236, v236, v245
	v_cvt_pk_bf16_f32 v194, v48, v49
	v_cvt_pk_bf16_f32 v195, v50, v51
	v_mul_f32_e32 v246, v49, v49
	v_mul_f32_e32 v247, v51, v51
	v_fmac_f32_e32 v246, v48, v48
	v_fmac_f32_e32 v247, v50, v50
	v_add_f32_e32 v185, v246, v247
	v_cvt_pk_bf16_f32 v196, v40, v41
	v_cvt_pk_bf16_f32 v197, v42, v43
	v_mul_f32_e32 v246, v41, v41
	v_mul_f32_e32 v247, v43, v43
	v_fmac_f32_e32 v246, v40, v40
	v_fmac_f32_e32 v247, v42, v42
	v_add_f32_e32 v246, v246, v247
	v_add_f32_e32 v185, v246, v185
	v_permlane16_swap_b32_e32 v194, v196
	v_permlane16_swap_b32_e32 v195, v197
	global_store_dwordx4 v236, v[194:197], s[22:23]
	s_nop 1
	v_cvt_pk_bf16_f32 v194, v36, v37
	v_cvt_pk_bf16_f32 v195, v38, v39
	v_mul_f32_e32 v246, v37, v37
	v_mul_f32_e32 v247, v39, v39
	v_fmac_f32_e32 v246, v36, v36
	v_fmac_f32_e32 v247, v38, v38
	v_add_f32_e32 v246, v246, v247
	v_add_f32_e32 v185, v246, v185
	v_cvt_pk_bf16_f32 v196, v28, v29
	v_cvt_pk_bf16_f32 v197, v30, v31
	v_mul_f32_e32 v246, v29, v29
	v_mul_f32_e32 v247, v31, v31
	v_fmac_f32_e32 v246, v28, v28
	v_fmac_f32_e32 v247, v30, v30
	v_add_f32_e32 v246, v246, v247
	v_add_f32_e32 v185, v246, v185
	v_permlane16_swap_b32_e32 v194, v196
	v_permlane16_swap_b32_e32 v195, v197
	global_store_dwordx4 v236, v[194:197], s[22:23] offset:256
	s_nop 1
	s_waitcnt vmcnt(22)
	v_pk_add_f32 v[32:33], v[128:129], v[32:33]
	v_pk_add_f32 v[34:35], v[130:131], v[34:35]
	v_pk_add_f32 v[24:25], v[132:133], v[24:25]
	v_pk_add_f32 v[26:27], v[134:135], v[26:27]
	v_pk_add_f32 v[20:21], v[136:137], v[20:21]
	v_pk_add_f32 v[22:23], v[138:139], v[22:23]
	v_pk_add_f32 v[12:13], v[140:141], v[12:13]
	v_pk_add_f32 v[14:15], v[142:143], v[14:15]
	v_add_u32_e32 v236, v192, v234
	v_add_u32_e32 v237, v192, v235
	v_mov_b32_dpp v222, v24 row_ror:8 row_mask:0xf bank_mask:0xf
	v_mov_b32_dpp v223, v25 row_ror:8 row_mask:0xf bank_mask:0xf
	v_mov_b32_dpp v224, v26 row_ror:8 row_mask:0xf bank_mask:0xf
	v_mov_b32_dpp v225, v27 row_ror:8 row_mask:0xf bank_mask:0xf
	v_cndmask_b32_e32 v226, v222, v32, vcc
	v_cndmask_b32_e32 v227, v223, v33, vcc
	v_cndmask_b32_e32 v228, v224, v34, vcc
	v_cndmask_b32_e32 v229, v225, v35, vcc
	v_cndmask_b32_e32 v230, v32, v222, vcc
	v_cndmask_b32_e32 v231, v33, v223, vcc
	v_cndmask_b32_e32 v232, v34, v224, vcc
	v_cndmask_b32_e32 v233, v35, v225, vcc
	global_store_dwordx4 v236, v[226:229], s[72:73]
	global_store_dwordx4 v237, v[230:233], s[72:73]
	v_mov_b32_dpp v222, v12 row_ror:8 row_mask:0xf bank_mask:0xf
	v_mov_b32_dpp v223, v13 row_ror:8 row_mask:0xf bank_mask:0xf
	v_mov_b32_dpp v224, v14 row_ror:8 row_mask:0xf bank_mask:0xf
	v_mov_b32_dpp v225, v15 row_ror:8 row_mask:0xf bank_mask:0xf
	v_cndmask_b32_e32 v226, v222, v20, vcc
	v_cndmask_b32_e32 v227, v223, v21, vcc
	v_cndmask_b32_e32 v228, v224, v22, vcc
	v_cndmask_b32_e32 v229, v225, v23, vcc
	v_cndmask_b32_e32 v230, v20, v222, vcc
	v_cndmask_b32_e32 v231, v21, v223, vcc
	v_cndmask_b32_e32 v232, v22, v224, vcc
	v_cndmask_b32_e32 v233, v23, v225, vcc
	global_store_dwordx4 v236, v[226:229], s[72:73] offset:512
	global_store_dwordx4 v237, v[230:233], s[72:73] offset:512
	v_lshrrev_b32_e32 v236, 1, v192
	v_add_u32_e32 v236, v236, v245
	v_cvt_pk_bf16_f32 v194, v32, v33
	v_cvt_pk_bf16_f32 v195, v34, v35
	v_mul_f32_e32 v246, v33, v33
	v_mul_f32_e32 v247, v35, v35
	v_fmac_f32_e32 v246, v32, v32
	v_fmac_f32_e32 v247, v34, v34
	v_add_f32_e32 v186, v246, v247
	v_cvt_pk_bf16_f32 v196, v24, v25
	v_cvt_pk_bf16_f32 v197, v26, v27
	v_mul_f32_e32 v246, v25, v25
	v_mul_f32_e32 v247, v27, v27
	v_fmac_f32_e32 v246, v24, v24
	v_fmac_f32_e32 v247, v26, v26
	v_add_f32_e32 v246, v246, v247
	v_add_f32_e32 v186, v246, v186
	v_permlane16_swap_b32_e32 v194, v196
	v_permlane16_swap_b32_e32 v195, v197
	global_store_dwordx4 v236, v[194:197], s[22:23]
	s_nop 1
	v_cvt_pk_bf16_f32 v194, v20, v21
	v_cvt_pk_bf16_f32 v195, v22, v23
	v_mul_f32_e32 v246, v21, v21
	v_mul_f32_e32 v247, v23, v23
	v_fmac_f32_e32 v246, v20, v20
	v_fmac_f32_e32 v247, v22, v22
	v_add_f32_e32 v246, v246, v247
	v_add_f32_e32 v186, v246, v186
	v_cvt_pk_bf16_f32 v196, v12, v13
	v_cvt_pk_bf16_f32 v197, v14, v15
	v_mul_f32_e32 v246, v13, v13
	v_mul_f32_e32 v247, v15, v15
	v_fmac_f32_e32 v246, v12, v12
	v_fmac_f32_e32 v247, v14, v14
	v_add_f32_e32 v246, v246, v247
	v_add_f32_e32 v186, v246, v186
	v_permlane16_swap_b32_e32 v194, v196
	v_permlane16_swap_b32_e32 v195, v197
	global_store_dwordx4 v236, v[194:197], s[22:23] offset:256
	s_nop 1
	s_waitcnt vmcnt(18)
; __device__ __forceinline__ unsigned cvt_pk_bf16(float lo, float hi) { unsigned r; asm volatile("v_cvt_pk_bf16_f32 %0, %1, %2" : "=v"(r) : "v"(lo), "v"(hi)); return r; }
;     __device__ __forceinline__ void operator()(const f32x4 (&acc)[2][2][4][2], const Unit& u, int wr, int wc, int fr, int fq) const {
;     ...
;             float sq = 0.f;
; #pragma unroll
;             for (int q = 0; q < 4; ++q) {
;                 const int bj = q >> 1, n = q & 1;
;                 const f32x4 o = bs[gi & 1][q] + acc[ai][bj][m][n];
;                 *(f32x4*)(out + off + bj * HALF + n * 16) = o;
;                 if (ss) {
;                     u32x2 w; w.x = cvt_pk_bf16(o[0], o[1]); w.y = cvt_pk_bf16(o[2], o[3]);
;                     *(u32x2*)(xb + off + bj * HALF + n * 16) = w;
;                     sq += (o[0] * o[0] + o[1] * o[1]) + (o[2] * o[2] + o[3] * o[3]);
;                 }
;             }
;             if (ss) { sq += __shfl_xor(sq, 16); sq += __shfl_xor(sq, 32); if (fq == 0) ss[(size_t)row * 32 + u.pn * 4 + wc] = sq; }
	v_pk_add_f32 v[16:17], v[144:145], v[16:17]
	v_pk_add_f32 v[18:19], v[146:147], v[18:19]
	v_pk_add_f32 v[8:9], v[148:149], v[8:9]
	v_pk_add_f32 v[10:11], v[150:151], v[10:11]
	v_pk_add_f32 v[4:5], v[152:153], v[4:5]
	v_pk_add_f32 v[6:7], v[154:155], v[6:7]
	v_pk_add_f32 v[0:1], v[156:157], v[0:1]
	v_pk_add_f32 v[2:3], v[158:159], v[2:3]
	v_add_u32_e32 v236, v193, v234
	v_add_u32_e32 v237, v193, v235
	v_mov_b32_dpp v222, v8 row_ror:8 row_mask:0xf bank_mask:0xf
	v_mov_b32_dpp v223, v9 row_ror:8 row_mask:0xf bank_mask:0xf
	v_mov_b32_dpp v224, v10 row_ror:8 row_mask:0xf bank_mask:0xf
	v_mov_b32_dpp v225, v11 row_ror:8 row_mask:0xf bank_mask:0xf
	v_cndmask_b32_e32 v226, v222, v16, vcc
	v_cndmask_b32_e32 v227, v223, v17, vcc
	v_cndmask_b32_e32 v228, v224, v18, vcc
	v_cndmask_b32_e32 v229, v225, v19, vcc
	v_cndmask_b32_e32 v230, v16, v222, vcc
	v_cndmask_b32_e32 v231, v17, v223, vcc
	v_cndmask_b32_e32 v232, v18, v224, vcc
	v_cndmask_b32_e32 v233, v19, v225, vcc
	global_store_dwordx4 v236, v[226:229], s[72:73]
	global_store_dwordx4 v237, v[230:233], s[72:73]
	v_mov_b32_dpp v222, v0 row_ror:8 row_mask:0xf bank_mask:0xf
	v_mov_b32_dpp v223, v1 row_ror:8 row_mask:0xf bank_mask:0xf
	v_mov_b32_dpp v224, v2 row_ror:8 row_mask:0xf bank_mask:0xf
	v_mov_b32_dpp v225, v3 row_ror:8 row_mask:0xf bank_mask:0xf
	v_cndmask_b32_e32 v226, v222, v4, vcc
	v_cndmask_b32_e32 v227, v223, v5, vcc
	v_cndmask_b32_e32 v228, v224, v6, vcc
	v_cndmask_b32_e32 v229, v225, v7, vcc
	v_cndmask_b32_e32 v230, v4, v222, vcc
	v_cndmask_b32_e32 v231, v5, v223, vcc
	v_cndmask_b32_e32 v232, v6, v224, vcc
	v_cndmask_b32_e32 v233, v7, v225, vcc
	global_store_dwordx4 v236, v[226:229], s[72:73] offset:512
	global_store_dwordx4 v237, v[230:233], s[72:73] offset:512
	v_lshrrev_b32_e32 v236, 1, v193
	v_add_u32_e32 v236, v236, v245
	v_cvt_pk_bf16_f32 v194, v16, v17
	v_cvt_pk_bf16_f32 v195, v18, v19
	v_mul_f32_e32 v246, v17, v17
	v_mul_f32_e32 v247, v19, v19
	v_fmac_f32_e32 v246, v16, v16
	v_fmac_f32_e32 v247, v18, v18
	v_add_f32_e32 v187, v246, v247
	v_cvt_pk_bf16_f32 v196, v8, v9
	v_cvt_pk_bf16_f32 v197, v10, v11
	v_mul_f32_e32 v246, v9, v9
	v_mul_f32_e32 v247, v11, v11
	v_fmac_f32_e32 v246, v8, v8
	v_fmac_f32_e32 v247, v10, v10
	v_add_f32_e32 v246, v246, v247
	v_add_f32_e32 v187, v246, v187
	v_permlane16_swap_b32_e32 v194, v196
	v_permlane16_swap_b32_e32 v195, v197
	global_store_dwordx4 v236, v[194:197], s[22:23]
	s_nop 1
	v_cvt_pk_bf16_f32 v194, v4, v5
	v_cvt_pk_bf16_f32 v195, v6, v7
	v_mul_f32_e32 v246, v5, v5
	v_mul_f32_e32 v247, v7, v7
	v_fmac_f32_e32 v246, v4, v4
	v_fmac_f32_e32 v247, v6, v6
	v_add_f32_e32 v246, v246, v247
	v_add_f32_e32 v187, v246, v187
	v_cvt_pk_bf16_f32 v196, v0, v1
	v_cvt_pk_bf16_f32 v197, v2, v3
	v_mul_f32_e32 v246, v1, v1
	v_mul_f32_e32 v247, v3, v3
	v_fmac_f32_e32 v246, v0, v0
	v_fmac_f32_e32 v247, v2, v2
	v_add_f32_e32 v246, v246, v247
	v_add_f32_e32 v187, v246, v187
	v_permlane16_swap_b32_e32 v194, v196
	v_permlane16_swap_b32_e32 v195, v197
	global_store_dwordx4 v236, v[194:197], s[22:23] offset:256
	s_nop 1
	v_xor_b32_e32 v246, 16, v167
	v_xor_b32_e32 v247, 32, v167
	v_lshlrev_b32_e32 v246, 2, v246
	v_lshlrev_b32_e32 v247, 2, v247
	ds_bpermute_b32 v128, v246, v180
	ds_bpermute_b32 v129, v246, v181
	ds_bpermute_b32 v130, v246, v182
	ds_bpermute_b32 v131, v246, v183
	ds_bpermute_b32 v132, v246, v184
	ds_bpermute_b32 v133, v246, v185
	ds_bpermute_b32 v134, v246, v186
	ds_bpermute_b32 v135, v246, v187
	s_waitcnt lgkmcnt(0)
	v_add_f32_e32 v180, v180, v128
	v_add_f32_e32 v181, v181, v129
	v_add_f32_e32 v182, v182, v130
	v_add_f32_e32 v183, v183, v131
	v_add_f32_e32 v184, v184, v132
	v_add_f32_e32 v185, v185, v133
	v_add_f32_e32 v186, v186, v134
	v_add_f32_e32 v187, v187, v135
	ds_bpermute_b32 v128, v247, v180
	ds_bpermute_b32 v129, v247, v181
	ds_bpermute_b32 v130, v247, v182
	ds_bpermute_b32 v131, v247, v183
	ds_bpermute_b32 v132, v247, v184
	ds_bpermute_b32 v133, v247, v185
	ds_bpermute_b32 v134, v247, v186
	ds_bpermute_b32 v135, v247, v187
	s_waitcnt lgkmcnt(0)
	v_add_f32_e32 v180, v180, v128
	v_add_f32_e32 v181, v181, v129
	v_add_f32_e32 v182, v182, v130
	v_add_f32_e32 v183, v183, v131
	v_add_f32_e32 v184, v184, v132
	v_add_f32_e32 v185, v185, v133
	v_add_f32_e32 v186, v186, v134
	v_add_f32_e32 v187, v187, v135
	v_add_u32_e32 v136, 0x0, v189
	v_add_u32_e32 v137, 0x800, v189
	v_add_u32_e32 v138, 0x1000, v189
	v_add_u32_e32 v139, 0x1800, v189
	v_add_u32_e32 v140, 0x4000, v189
	v_add_u32_e32 v141, 0x4800, v189
	v_add_u32_e32 v142, 0x5000, v189
	v_add_u32_e32 v143, 0x5800, v189
	s_and_saveexec_b64 s[36:37], s[0:1]
	global_store_dword v136, v180, s[10:11]
	global_store_dword v137, v181, s[10:11]
	global_store_dword v138, v182, s[10:11]
	global_store_dword v139, v183, s[10:11]
	global_store_dword v140, v184, s[10:11]
	global_store_dword v141, v185, s[10:11]
	global_store_dword v142, v186, s[10:11]
	global_store_dword v143, v187, s[10:11]
	s_or_b64 exec, exec, s[36:37]
	s_branch .LBB0_385
;     __device__ __forceinline__ void operator()(const f32x4 (&acc)[2][2][4][2], const Unit& u, int wr, int wc, int fr, int fq) const {
;         const int row0 = u.pm * BM + wr * 64 + fr, col0 = u.pn * BM + wc * 32 + 4 * fq;
;         f32x4 bs[2][4];
; #pragma unroll
;         for (int q = 0; q < 4; ++q) bs[0][q] = *(const f32x4*)(xin + (size_t)row0 * ldc + col0 + (q >> 1) * HALF + (q & 1) * 16);
; #pragma unroll
;         for (int gi = 0; gi < 8; ++gi) {
;             const int ai = gi >> 2, m = gi & 3;
;             const int row = row0 + ai * HALF + m * 16;
;             const size_t off = (size_t)row * ldc + col0;
;             if (gi + 1 < 8) {
;                 const size_t offn = (size_t)(row0 + ((gi + 1) >> 2) * HALF + ((gi + 1) & 3) * 16) * ldc + col0;
; #pragma unroll
;                 for (int q = 0; q < 4; ++q) bs[(gi + 1) & 1][q] = *(const f32x4*)(xin + offn + (q >> 1) * HALF + (q & 1) * 16);
;             }
;             float sq = 0.f;
; #pragma unroll
;             for (int q = 0; q < 4; ++q) {
;                 const int bj = q >> 1, n = q & 1;
;                 const f32x4 o = bs[gi & 1][q] + acc[ai][bj][m][n];
;                 *(f32x4*)(out + off + bj * HALF + n * 16) = o;
.Lres_noss:
	v_lshl_add_u32 v246, s55, 8, v188
	v_lshl_or_b32 v247, s2, 8, v190
	v_lshlrev_b32_e32 v247, 2, v247
	v_lshl_add_u32 v160, v246, 13, v247
	v_add_u32_e32 v161, 0x20000, v160
	v_add_u32_e32 v162, 0x40000, v160
	v_add_u32_e32 v163, 0x60000, v160
	v_add_u32_e32 v164, 0x100000, v160
	v_add_u32_e32 v165, 0x120000, v160
	v_add_u32_e32 v192, 0x140000, v160
	v_add_u32_e32 v193, 0x160000, v160
	global_load_dwordx4 v[128:131], v160, s[14:15]
	global_load_dwordx4 v[132:135], v160, s[14:15] offset:64
	global_load_dwordx4 v[136:139], v160, s[14:15] offset:512
	global_load_dwordx4 v[140:143], v160, s[14:15] offset:576
	global_load_dwordx4 v[144:147], v161, s[14:15]
	global_load_dwordx4 v[148:151], v161, s[14:15] offset:64
	global_load_dwordx4 v[152:155], v161, s[14:15] offset:512
	global_load_dwordx4 v[156:159], v161, s[14:15] offset:576
	global_load_dwordx4 v[206:209], v162, s[14:15]
	global_load_dwordx4 v[210:213], v162, s[14:15] offset:64
	global_load_dwordx4 v[214:217], v162, s[14:15] offset:512
	global_load_dwordx4 v[218:221], v162, s[14:15] offset:576
	v_and_b32_e32 v246, 8, v188
	v_mov_b32_e32 v247, 0x10040
	v_cmp_eq_u32_e32 vcc, 0, v246
	s_nop 1
	v_mov_b32_e32 v246, 0xffff0040
	v_cndmask_b32_e32 v234, v246, v169, vcc
	v_cndmask_b32_e32 v235, 0, v247, vcc
	s_waitcnt vmcnt(8)
	v_pk_add_f32 v[124:125], v[128:129], v[124:125]
	v_pk_add_f32 v[126:127], v[130:131], v[126:127]
	v_pk_add_f32 v[120:121], v[132:133], v[120:121]
	v_pk_add_f32 v[122:123], v[134:135], v[122:123]
	v_pk_add_f32 v[116:117], v[136:137], v[116:117]
	v_pk_add_f32 v[118:119], v[138:139], v[118:119]
	v_pk_add_f32 v[108:109], v[140:141], v[108:109]
	v_pk_add_f32 v[110:111], v[142:143], v[110:111]
	global_load_dwordx4 v[128:131], v163, s[14:15]
	global_load_dwordx4 v[132:135], v163, s[14:15] offset:64
	global_load_dwordx4 v[136:139], v163, s[14:15] offset:512
	global_load_dwordx4 v[140:143], v163, s[14:15] offset:576
	v_add_u32_e32 v236, v160, v234
	v_add_u32_e32 v237, v160, v235
	v_mov_b32_dpp v222, v120 row_ror:8 row_mask:0xf bank_mask:0xf
	v_mov_b32_dpp v223, v121 row_ror:8 row_mask:0xf bank_mask:0xf
	v_mov_b32_dpp v224, v122 row_ror:8 row_mask:0xf bank_mask:0xf
	v_mov_b32_dpp v225, v123 row_ror:8 row_mask:0xf bank_mask:0xf
	v_cndmask_b32_e32 v226, v222, v124, vcc
	v_cndmask_b32_e32 v227, v223, v125, vcc
	v_cndmask_b32_e32 v228, v224, v126, vcc
	v_cndmask_b32_e32 v229, v225, v127, vcc
	v_cndmask_b32_e32 v230, v124, v222, vcc
	v_cndmask_b32_e32 v231, v125, v223, vcc
	v_cndmask_b32_e32 v232, v126, v224, vcc
	v_cndmask_b32_e32 v233, v127, v225, vcc
	global_store_dwordx4 v236, v[226:229], s[72:73]
	global_store_dwordx4 v237, v[230:233], s[72:73]
	v_mov_b32_dpp v222, v108 row_ror:8 row_mask:0xf bank_mask:0xf
	v_mov_b32_dpp v223, v109 row_ror:8 row_mask:0xf bank_mask:0xf
	v_mov_b32_dpp v224, v110 row_ror:8 row_mask:0xf bank_mask:0xf
	v_mov_b32_dpp v225, v111 row_ror:8 row_mask:0xf bank_mask:0xf
	v_cndmask_b32_e32 v226, v222, v116, vcc
	v_cndmask_b32_e32 v227, v223, v117, vcc
	v_cndmask_b32_e32 v228, v224, v118, vcc
	v_cndmask_b32_e32 v229, v225, v119, vcc
	v_cndmask_b32_e32 v230, v116, v222, vcc
	v_cndmask_b32_e32 v231, v117, v223, vcc
	v_cndmask_b32_e32 v232, v118, v224, vcc
	v_cndmask_b32_e32 v233, v119, v225, vcc
	global_store_dwordx4 v236, v[226:229], s[72:73] offset:512
	global_store_dwordx4 v237, v[230:233], s[72:73] offset:512
	s_waitcnt vmcnt(12)
	v_pk_add_f32 v[112:113], v[144:145], v[112:113]
	v_pk_add_f32 v[114:115], v[146:147], v[114:115]
	v_pk_add_f32 v[104:105], v[148:149], v[104:105]
	v_pk_add_f32 v[106:107], v[150:151], v[106:107]
	v_pk_add_f32 v[100:101], v[152:153], v[100:101]
	v_pk_add_f32 v[102:103], v[154:155], v[102:103]
	v_pk_add_f32 v[92:93], v[156:157], v[92:93]
	v_pk_add_f32 v[94:95], v[158:159], v[94:95]
	global_load_dwordx4 v[144:147], v164, s[14:15]
	global_load_dwordx4 v[148:151], v164, s[14:15] offset:64
	global_load_dwordx4 v[152:155], v164, s[14:15] offset:512
	global_load_dwordx4 v[156:159], v164, s[14:15] offset:576
	v_add_u32_e32 v236, v161, v234
	v_add_u32_e32 v237, v161, v235
	v_mov_b32_dpp v222, v104 row_ror:8 row_mask:0xf bank_mask:0xf
	v_mov_b32_dpp v223, v105 row_ror:8 row_mask:0xf bank_mask:0xf
	v_mov_b32_dpp v224, v106 row_ror:8 row_mask:0xf bank_mask:0xf
	v_mov_b32_dpp v225, v107 row_ror:8 row_mask:0xf bank_mask:0xf
	v_cndmask_b32_e32 v226, v222, v112, vcc
	v_cndmask_b32_e32 v227, v223, v113, vcc
	v_cndmask_b32_e32 v228, v224, v114, vcc
	v_cndmask_b32_e32 v229, v225, v115, vcc
	v_cndmask_b32_e32 v230, v112, v222, vcc
	v_cndmask_b32_e32 v231, v113, v223, vcc
	v_cndmask_b32_e32 v232, v114, v224, vcc
	v_cndmask_b32_e32 v233, v115, v225, vcc
	global_store_dwordx4 v236, v[226:229], s[72:73]
	global_store_dwordx4 v237, v[230:233], s[72:73]
	v_mov_b32_dpp v222, v92 row_ror:8 row_mask:0xf bank_mask:0xf
	v_mov_b32_dpp v223, v93 row_ror:8 row_mask:0xf bank_mask:0xf
	v_mov_b32_dpp v224, v94 row_ror:8 row_mask:0xf bank_mask:0xf
	v_mov_b32_dpp v225, v95 row_ror:8 row_mask:0xf bank_mask:0xf
	v_cndmask_b32_e32 v226, v222, v100, vcc
	v_cndmask_b32_e32 v227, v223, v101, vcc
	v_cndmask_b32_e32 v228, v224, v102, vcc
	v_cndmask_b32_e32 v229, v225, v103, vcc
	v_cndmask_b32_e32 v230, v100, v222, vcc
	v_cndmask_b32_e32 v231, v101, v223, vcc
	v_cndmask_b32_e32 v232, v102, v224, vcc
	v_cndmask_b32_e32 v233, v103, v225, vcc
	global_store_dwordx4 v236, v[226:229], s[72:73] offset:512
	global_store_dwordx4 v237, v[230:233], s[72:73] offset:512
	s_waitcnt vmcnt(16)
;     __device__ __forceinline__ void operator()(const f32x4 (&acc)[2][2][4][2], const Unit& u, int wr, int wc, int fr, int fq) const {
;     ...
;         for (int gi = 0; gi < 8; ++gi) {
;             const int ai = gi >> 2, m = gi & 3;
;             const int row = row0 + ai * HALF + m * 16;
;             const size_t off = (size_t)row * ldc + col0;
;             if (gi + 1 < 8) {
;                 const size_t offn = (size_t)(row0 + ((gi + 1) >> 2) * HALF + ((gi + 1) & 3) * 16) * ldc + col0;
; #pragma unroll
;                 for (int q = 0; q < 4; ++q) bs[(gi + 1) & 1][q] = *(const f32x4*)(xin + offn + (q >> 1) * HALF + (q & 1) * 16);
;             }
;             float sq = 0.f;
; #pragma unroll
;             for (int q = 0; q < 4; ++q) {
;                 const int bj = q >> 1, n = q & 1;
;                 const f32x4 o = bs[gi & 1][q] + acc[ai][bj][m][n];
;                 *(f32x4*)(out + off + bj * HALF + n * 16) = o;
	v_pk_add_f32 v[96:97], v[206:207], v[96:97]
	v_pk_add_f32 v[98:99], v[208:209], v[98:99]
	v_pk_add_f32 v[88:89], v[210:211], v[88:89]
	v_pk_add_f32 v[90:91], v[212:213], v[90:91]
	v_pk_add_f32 v[84:85], v[214:215], v[84:85]
	v_pk_add_f32 v[86:87], v[216:217], v[86:87]
	v_pk_add_f32 v[76:77], v[218:219], v[76:77]
	v_pk_add_f32 v[78:79], v[220:221], v[78:79]
	global_load_dwordx4 v[206:209], v165, s[14:15]
	global_load_dwordx4 v[210:213], v165, s[14:15] offset:64
	global_load_dwordx4 v[214:217], v165, s[14:15] offset:512
	global_load_dwordx4 v[218:221], v165, s[14:15] offset:576
	v_add_u32_e32 v236, v162, v234
	v_add_u32_e32 v237, v162, v235
	v_mov_b32_dpp v222, v88 row_ror:8 row_mask:0xf bank_mask:0xf
	v_mov_b32_dpp v223, v89 row_ror:8 row_mask:0xf bank_mask:0xf
	v_mov_b32_dpp v224, v90 row_ror:8 row_mask:0xf bank_mask:0xf
	v_mov_b32_dpp v225, v91 row_ror:8 row_mask:0xf bank_mask:0xf
	v_cndmask_b32_e32 v226, v222, v96, vcc
	v_cndmask_b32_e32 v227, v223, v97, vcc
	v_cndmask_b32_e32 v228, v224, v98, vcc
	v_cndmask_b32_e32 v229, v225, v99, vcc
	v_cndmask_b32_e32 v230, v96, v222, vcc
	v_cndmask_b32_e32 v231, v97, v223, vcc
	v_cndmask_b32_e32 v232, v98, v224, vcc
	v_cndmask_b32_e32 v233, v99, v225, vcc
	global_store_dwordx4 v236, v[226:229], s[72:73]
	global_store_dwordx4 v237, v[230:233], s[72:73]
	v_mov_b32_dpp v222, v76 row_ror:8 row_mask:0xf bank_mask:0xf
	v_mov_b32_dpp v223, v77 row_ror:8 row_mask:0xf bank_mask:0xf
	v_mov_b32_dpp v224, v78 row_ror:8 row_mask:0xf bank_mask:0xf
	v_mov_b32_dpp v225, v79 row_ror:8 row_mask:0xf bank_mask:0xf
	v_cndmask_b32_e32 v226, v222, v84, vcc
	v_cndmask_b32_e32 v227, v223, v85, vcc
	v_cndmask_b32_e32 v228, v224, v86, vcc
	v_cndmask_b32_e32 v229, v225, v87, vcc
	v_cndmask_b32_e32 v230, v84, v222, vcc
	v_cndmask_b32_e32 v231, v85, v223, vcc
	v_cndmask_b32_e32 v232, v86, v224, vcc
	v_cndmask_b32_e32 v233, v87, v225, vcc
	global_store_dwordx4 v236, v[226:229], s[72:73] offset:512
	global_store_dwordx4 v237, v[230:233], s[72:73] offset:512
	s_waitcnt vmcnt(20)
	v_pk_add_f32 v[80:81], v[128:129], v[80:81]
	v_pk_add_f32 v[82:83], v[130:131], v[82:83]
	v_pk_add_f32 v[72:73], v[132:133], v[72:73]
	v_pk_add_f32 v[74:75], v[134:135], v[74:75]
	v_pk_add_f32 v[68:69], v[136:137], v[68:69]
	v_pk_add_f32 v[70:71], v[138:139], v[70:71]
	v_pk_add_f32 v[64:65], v[140:141], v[64:65]
	v_pk_add_f32 v[66:67], v[142:143], v[66:67]
	global_load_dwordx4 v[128:131], v192, s[14:15]
	global_load_dwordx4 v[132:135], v192, s[14:15] offset:64
	global_load_dwordx4 v[136:139], v192, s[14:15] offset:512
	global_load_dwordx4 v[140:143], v192, s[14:15] offset:576
	v_add_u32_e32 v236, v163, v234
	v_add_u32_e32 v237, v163, v235
	v_mov_b32_dpp v222, v72 row_ror:8 row_mask:0xf bank_mask:0xf
	v_mov_b32_dpp v223, v73 row_ror:8 row_mask:0xf bank_mask:0xf
	v_mov_b32_dpp v224, v74 row_ror:8 row_mask:0xf bank_mask:0xf
	v_mov_b32_dpp v225, v75 row_ror:8 row_mask:0xf bank_mask:0xf
	v_cndmask_b32_e32 v226, v222, v80, vcc
	v_cndmask_b32_e32 v227, v223, v81, vcc
	v_cndmask_b32_e32 v228, v224, v82, vcc
	v_cndmask_b32_e32 v229, v225, v83, vcc
	v_cndmask_b32_e32 v230, v80, v222, vcc
	v_cndmask_b32_e32 v231, v81, v223, vcc
	v_cndmask_b32_e32 v232, v82, v224, vcc
	v_cndmask_b32_e32 v233, v83, v225, vcc
	global_store_dwordx4 v236, v[226:229], s[72:73]
	global_store_dwordx4 v237, v[230:233], s[72:73]
	v_mov_b32_dpp v222, v64 row_ror:8 row_mask:0xf bank_mask:0xf
	v_mov_b32_dpp v223, v65 row_ror:8 row_mask:0xf bank_mask:0xf
	v_mov_b32_dpp v224, v66 row_ror:8 row_mask:0xf bank_mask:0xf
	v_mov_b32_dpp v225, v67 row_ror:8 row_mask:0xf bank_mask:0xf
	v_cndmask_b32_e32 v226, v222, v68, vcc
	v_cndmask_b32_e32 v227, v223, v69, vcc
	v_cndmask_b32_e32 v228, v224, v70, vcc
	v_cndmask_b32_e32 v229, v225, v71, vcc
	v_cndmask_b32_e32 v230, v68, v222, vcc
	v_cndmask_b32_e32 v231, v69, v223, vcc
	v_cndmask_b32_e32 v232, v70, v224, vcc
	v_cndmask_b32_e32 v233, v71, v225, vcc
	global_store_dwordx4 v236, v[226:229], s[72:73] offset:512
	global_store_dwordx4 v237, v[230:233], s[72:73] offset:512
	s_waitcnt vmcnt(20)
	v_pk_add_f32 v[60:61], v[144:145], v[60:61]
	v_pk_add_f32 v[62:63], v[146:147], v[62:63]
	v_pk_add_f32 v[56:57], v[148:149], v[56:57]
	v_pk_add_f32 v[58:59], v[150:151], v[58:59]
	v_pk_add_f32 v[52:53], v[152:153], v[52:53]
	v_pk_add_f32 v[54:55], v[154:155], v[54:55]
	v_pk_add_f32 v[44:45], v[156:157], v[44:45]
	v_pk_add_f32 v[46:47], v[158:159], v[46:47]
	global_load_dwordx4 v[144:147], v193, s[14:15]
	global_load_dwordx4 v[148:151], v193, s[14:15] offset:64
	global_load_dwordx4 v[152:155], v193, s[14:15] offset:512
	global_load_dwordx4 v[156:159], v193, s[14:15] offset:576
	v_add_u32_e32 v236, v164, v234
	v_add_u32_e32 v237, v164, v235
	v_mov_b32_dpp v222, v56 row_ror:8 row_mask:0xf bank_mask:0xf
	v_mov_b32_dpp v223, v57 row_ror:8 row_mask:0xf bank_mask:0xf
	v_mov_b32_dpp v224, v58 row_ror:8 row_mask:0xf bank_mask:0xf
	v_mov_b32_dpp v225, v59 row_ror:8 row_mask:0xf bank_mask:0xf
	v_cndmask_b32_e32 v226, v222, v60, vcc
	v_cndmask_b32_e32 v227, v223, v61, vcc
	v_cndmask_b32_e32 v228, v224, v62, vcc
	v_cndmask_b32_e32 v229, v225, v63, vcc
	v_cndmask_b32_e32 v230, v60, v222, vcc
	v_cndmask_b32_e32 v231, v61, v223, vcc
	v_cndmask_b32_e32 v232, v62, v224, vcc
	v_cndmask_b32_e32 v233, v63, v225, vcc
	global_store_dwordx4 v236, v[226:229], s[72:73]
	global_store_dwordx4 v237, v[230:233], s[72:73]
	v_mov_b32_dpp v222, v44 row_ror:8 row_mask:0xf bank_mask:0xf
	v_mov_b32_dpp v223, v45 row_ror:8 row_mask:0xf bank_mask:0xf
	v_mov_b32_dpp v224, v46 row_ror:8 row_mask:0xf bank_mask:0xf
	v_mov_b32_dpp v225, v47 row_ror:8 row_mask:0xf bank_mask:0xf
	v_cndmask_b32_e32 v226, v222, v52, vcc
	v_cndmask_b32_e32 v227, v223, v53, vcc
	v_cndmask_b32_e32 v228, v224, v54, vcc
	v_cndmask_b32_e32 v229, v225, v55, vcc
	v_cndmask_b32_e32 v230, v52, v222, vcc
	v_cndmask_b32_e32 v231, v53, v223, vcc
	v_cndmask_b32_e32 v232, v54, v224, vcc
	v_cndmask_b32_e32 v233, v55, v225, vcc
	global_store_dwordx4 v236, v[226:229], s[72:73] offset:512
	global_store_dwordx4 v237, v[230:233], s[72:73] offset:512
	s_waitcnt vmcnt(20)
;     __device__ __forceinline__ void operator()(const f32x4 (&acc)[2][2][4][2], const Unit& u, int wr, int wc, int fr, int fq) const {
;     ...
;         for (int gi = 0; gi < 8; ++gi) {
;             const int ai = gi >> 2, m = gi & 3;
;             const int row = row0 + ai * HALF + m * 16;
;             const size_t off = (size_t)row * ldc + col0;
;             if (gi + 1 < 8) {
;                 const size_t offn = (size_t)(row0 + ((gi + 1) >> 2) * HALF + ((gi + 1) & 3) * 16) * ldc + col0;
; #pragma unroll
;                 for (int q = 0; q < 4; ++q) bs[(gi + 1) & 1][q] = *(const f32x4*)(xin + offn + (q >> 1) * HALF + (q & 1) * 16);
;             }
;             float sq = 0.f;
; #pragma unroll
;             for (int q = 0; q < 4; ++q) {
;                 const int bj = q >> 1, n = q & 1;
;                 const f32x4 o = bs[gi & 1][q] + acc[ai][bj][m][n];
;                 *(f32x4*)(out + off + bj * HALF + n * 16) = o;
	v_pk_add_f32 v[48:49], v[206:207], v[48:49]
	v_pk_add_f32 v[50:51], v[208:209], v[50:51]
	v_pk_add_f32 v[40:41], v[210:211], v[40:41]
	v_pk_add_f32 v[42:43], v[212:213], v[42:43]
	v_pk_add_f32 v[36:37], v[214:215], v[36:37]
	v_pk_add_f32 v[38:39], v[216:217], v[38:39]
	v_pk_add_f32 v[28:29], v[218:219], v[28:29]
	v_pk_add_f32 v[30:31], v[220:221], v[30:31]
	v_add_u32_e32 v236, v165, v234
	v_add_u32_e32 v237, v165, v235
	v_mov_b32_dpp v222, v40 row_ror:8 row_mask:0xf bank_mask:0xf
	v_mov_b32_dpp v223, v41 row_ror:8 row_mask:0xf bank_mask:0xf
	v_mov_b32_dpp v224, v42 row_ror:8 row_mask:0xf bank_mask:0xf
	v_mov_b32_dpp v225, v43 row_ror:8 row_mask:0xf bank_mask:0xf
	v_cndmask_b32_e32 v226, v222, v48, vcc
	v_cndmask_b32_e32 v227, v223, v49, vcc
	v_cndmask_b32_e32 v228, v224, v50, vcc
	v_cndmask_b32_e32 v229, v225, v51, vcc
	v_cndmask_b32_e32 v230, v48, v222, vcc
	v_cndmask_b32_e32 v231, v49, v223, vcc
	v_cndmask_b32_e32 v232, v50, v224, vcc
	v_cndmask_b32_e32 v233, v51, v225, vcc
	global_store_dwordx4 v236, v[226:229], s[72:73]
	global_store_dwordx4 v237, v[230:233], s[72:73]
	v_mov_b32_dpp v222, v28 row_ror:8 row_mask:0xf bank_mask:0xf
	v_mov_b32_dpp v223, v29 row_ror:8 row_mask:0xf bank_mask:0xf
	v_mov_b32_dpp v224, v30 row_ror:8 row_mask:0xf bank_mask:0xf
	v_mov_b32_dpp v225, v31 row_ror:8 row_mask:0xf bank_mask:0xf
	v_cndmask_b32_e32 v226, v222, v36, vcc
	v_cndmask_b32_e32 v227, v223, v37, vcc
	v_cndmask_b32_e32 v228, v224, v38, vcc
	v_cndmask_b32_e32 v229, v225, v39, vcc
	v_cndmask_b32_e32 v230, v36, v222, vcc
	v_cndmask_b32_e32 v231, v37, v223, vcc
	v_cndmask_b32_e32 v232, v38, v224, vcc
	v_cndmask_b32_e32 v233, v39, v225, vcc
	global_store_dwordx4 v236, v[226:229], s[72:73] offset:512
	global_store_dwordx4 v237, v[230:233], s[72:73] offset:512
	s_waitcnt vmcnt(16)
	v_pk_add_f32 v[32:33], v[128:129], v[32:33]
	v_pk_add_f32 v[34:35], v[130:131], v[34:35]
	v_pk_add_f32 v[24:25], v[132:133], v[24:25]
	v_pk_add_f32 v[26:27], v[134:135], v[26:27]
	v_pk_add_f32 v[20:21], v[136:137], v[20:21]
	v_pk_add_f32 v[22:23], v[138:139], v[22:23]
	v_pk_add_f32 v[12:13], v[140:141], v[12:13]
	v_pk_add_f32 v[14:15], v[142:143], v[14:15]
	v_add_u32_e32 v236, v192, v234
	v_add_u32_e32 v237, v192, v235
	v_mov_b32_dpp v222, v24 row_ror:8 row_mask:0xf bank_mask:0xf
	v_mov_b32_dpp v223, v25 row_ror:8 row_mask:0xf bank_mask:0xf
	v_mov_b32_dpp v224, v26 row_ror:8 row_mask:0xf bank_mask:0xf
	v_mov_b32_dpp v225, v27 row_ror:8 row_mask:0xf bank_mask:0xf
	v_cndmask_b32_e32 v226, v222, v32, vcc
	v_cndmask_b32_e32 v227, v223, v33, vcc
	v_cndmask_b32_e32 v228, v224, v34, vcc
	v_cndmask_b32_e32 v229, v225, v35, vcc
	v_cndmask_b32_e32 v230, v32, v222, vcc
	v_cndmask_b32_e32 v231, v33, v223, vcc
	v_cndmask_b32_e32 v232, v34, v224, vcc
	v_cndmask_b32_e32 v233, v35, v225, vcc
	global_store_dwordx4 v236, v[226:229], s[72:73]
	global_store_dwordx4 v237, v[230:233], s[72:73]
	v_mov_b32_dpp v222, v12 row_ror:8 row_mask:0xf bank_mask:0xf
	v_mov_b32_dpp v223, v13 row_ror:8 row_mask:0xf bank_mask:0xf
	v_mov_b32_dpp v224, v14 row_ror:8 row_mask:0xf bank_mask:0xf
	v_mov_b32_dpp v225, v15 row_ror:8 row_mask:0xf bank_mask:0xf
	v_cndmask_b32_e32 v226, v222, v20, vcc
	v_cndmask_b32_e32 v227, v223, v21, vcc
	v_cndmask_b32_e32 v228, v224, v22, vcc
	v_cndmask_b32_e32 v229, v225, v23, vcc
	v_cndmask_b32_e32 v230, v20, v222, vcc
	v_cndmask_b32_e32 v231, v21, v223, vcc
	v_cndmask_b32_e32 v232, v22, v224, vcc
	v_cndmask_b32_e32 v233, v23, v225, vcc
	global_store_dwordx4 v236, v[226:229], s[72:73] offset:512
	global_store_dwordx4 v237, v[230:233], s[72:73] offset:512
	s_waitcnt vmcnt(12)
	v_pk_add_f32 v[16:17], v[144:145], v[16:17]
	v_pk_add_f32 v[18:19], v[146:147], v[18:19]
	v_pk_add_f32 v[8:9], v[148:149], v[8:9]
	v_pk_add_f32 v[10:11], v[150:151], v[10:11]
	v_pk_add_f32 v[4:5], v[152:153], v[4:5]
	v_pk_add_f32 v[6:7], v[154:155], v[6:7]
	v_pk_add_f32 v[0:1], v[156:157], v[0:1]
	v_pk_add_f32 v[2:3], v[158:159], v[2:3]
	v_add_u32_e32 v236, v193, v234
	v_add_u32_e32 v237, v193, v235
	v_mov_b32_dpp v222, v8 row_ror:8 row_mask:0xf bank_mask:0xf
	v_mov_b32_dpp v223, v9 row_ror:8 row_mask:0xf bank_mask:0xf
	v_mov_b32_dpp v224, v10 row_ror:8 row_mask:0xf bank_mask:0xf
	v_mov_b32_dpp v225, v11 row_ror:8 row_mask:0xf bank_mask:0xf
	v_cndmask_b32_e32 v226, v222, v16, vcc
	v_cndmask_b32_e32 v227, v223, v17, vcc
	v_cndmask_b32_e32 v228, v224, v18, vcc
	v_cndmask_b32_e32 v229, v225, v19, vcc
	v_cndmask_b32_e32 v230, v16, v222, vcc
	v_cndmask_b32_e32 v231, v17, v223, vcc
	v_cndmask_b32_e32 v232, v18, v224, vcc
	v_cndmask_b32_e32 v233, v19, v225, vcc
	global_store_dwordx4 v236, v[226:229], s[72:73]
	global_store_dwordx4 v237, v[230:233], s[72:73]
	v_mov_b32_dpp v222, v0 row_ror:8 row_mask:0xf bank_mask:0xf
	v_mov_b32_dpp v223, v1 row_ror:8 row_mask:0xf bank_mask:0xf
	v_mov_b32_dpp v224, v2 row_ror:8 row_mask:0xf bank_mask:0xf
	v_mov_b32_dpp v225, v3 row_ror:8 row_mask:0xf bank_mask:0xf
	v_cndmask_b32_e32 v226, v222, v4, vcc
	v_cndmask_b32_e32 v227, v223, v5, vcc
	v_cndmask_b32_e32 v228, v224, v6, vcc
	v_cndmask_b32_e32 v229, v225, v7, vcc
	v_cndmask_b32_e32 v230, v4, v222, vcc
	v_cndmask_b32_e32 v231, v5, v223, vcc
	v_cndmask_b32_e32 v232, v6, v224, vcc
	v_cndmask_b32_e32 v233, v7, v225, vcc
	global_store_dwordx4 v236, v[226:229], s[72:73] offset:512
	global_store_dwordx4 v237, v[230:233], s[72:73] offset:512
